# plus: SSD staging blocks: 15 of 16 redundant per-block reloads of a spilled SGPR pair removed (issue work off the critical mixer item)
# baseline (speedup 1.0000x reference)
; #define LAS __attribute__((address_space(3)))
; __device__ __forceinline__ unsigned pk2(float lo, float hi) { return pg8::cvt_pk_bf16(lo, hi); }
; __device__ __forceinline__ void ssd_item(LAS unsigned char* lds, const bf16* proj, const bf16* cxb, bf16* yout, const float* dt_bias, const float* a_log, const float* dskip,
;                                          int gv, int vloc, int hh, int dir) {
;     ...
;             for (int hc = 0; hc < 2; ++hc) {
;                 u32x2 pv[4];
; #pragma unroll
;                 for (int od = 0; od < 8; ++od) {
;                     u32x2 pk; pk.x = raw[od][2 * hc]; pk.y = raw[od][2 * hc + 1];
;                     if (sec == 0) pv[od & 3] = pk;
;                     else if (sec == 1) { *(LAS u32x2*)(BN + (i0 + od) * LDS_ + c8 + 4 * hc) = pk; const float wr = __expf(tot - ACUM[i0 + od]) * DT[i0 + od];
;                         u32x2 pw; pw.x = pk2(bflo(pk.x) * wr, bfhi(pk.x) * wr); pw.y = pk2(bflo(pk.y) * wr, bfhi(pk.y) * wr); pv[od & 3] = pw; }
;                     else *(LAS u32x2*)(CN + (i0 + od) * LDS_ + c8 + 4 * hc) = pk;
;                     if ((od & 3) == 3 && sec != 2) {
;                         LAS bf16* dstT = (sec == 0 ? XST : BTW) + (c8 + 4 * hc) * LDL + i0 + (od - 3);
; #pragma unroll
;                         for (int m = 0; m < 2; ++m) {
;                             u32x2 we, wo;
;                             we.x = (pv[0][m] & 0xffffu) | (pv[1][m] << 16); we.y = (pv[2][m] & 0xffffu) | (pv[3][m] << 16);
;                             wo.x = (pv[0][m] >> 16) | (pv[1][m] & 0xffff0000u); wo.y = (pv[2][m] >> 16) | (pv[3][m] & 0xffff0000u);
;                             *(LAS u32x2*)(dstT + (2 * m) * LDL) = we; *(LAS u32x2*)(dstT + (2 * m + 1) * LDL) = wo;
;                         }
;                     }
;                 }
.LBB0_557:
	s_or_b64 exec, exec, s[50:51]
	s_andn2_saveexec_b64 s[0:1], s[0:1]
	s_cbranch_execz .LBB0_503
